# gemm1 epilogue stores use sc1 write-through policy
# speedup vs baseline: 1.0080x; 1.0080x over previous
; __device__ __forceinline__ unsigned cvt_pk_bf16(float lo, float hi) { unsigned r; asm volatile("v_cvt_pk_bf16_f32 %0, %1, %2" : "=v"(r) : "v"(lo), "v"(hi)); return r; }
;     __device__ __forceinline__ void operator()(const f32x4 (&acc)[2][2][4][2], const Unit& u, int wr, int wc, int fr, int fq) const {
;         const int row0 = u.pm * BM + wr * 64 + fr;
;         const bool second = u.pn >= split;
;         bf16_t* base = second ? O1 : O0; const int ld = second ? ld1 : ld0;
;         const int col0 = (second ? (u.pn - split) : u.pn) * BM + wc * 32 + 8 * fq;
;         const bool sig = second && (bias1 != nullptr);
;         f32x4 bv[2][2];
; #pragma unroll
;         for (int bj = 0; bj < 2; ++bj)
; #pragma unroll
;             for (int n = 0; n < 2; ++n) bv[bj][n] = sig ? *(const f32x4*)(bias1 + col0 + bj * HALF + 4 * n) : (f32x4){0.f, 0.f, 0.f, 0.f};
; #pragma unroll
;         for (int ai = 0; ai < 2; ++ai)
; #pragma unroll
;             for (int m = 0; m < 4; ++m) { bf16_t* rowp = base + (size_t)(row0 + ai * HALF + m * 16) * ld + col0;
; #pragma unroll
;                 for (int bj = 0; bj < 2; ++bj) { f32x4 v0 = acc[ai][bj][m][0] + bv[bj][0], v1 = acc[ai][bj][m][1] + bv[bj][1];
;                     if (sig) {
; #pragma unroll
;                         for (int j = 0; j < 4; ++j) { v0[j] = __builtin_amdgcn_rcpf(1.0f + __expf(-v0[j])); v1[j] = __builtin_amdgcn_rcpf(1.0f + __expf(-v1[j])); } }
;                     u32x4 w; w.x = cvt_pk_bf16(v0[0], v0[1]); w.y = cvt_pk_bf16(v0[2], v0[3]); w.z = cvt_pk_bf16(v1[0], v1[1]); w.w = cvt_pk_bf16(v1[2], v1[3]);
;                     *(u32x4*)(rowp + bj * HALF) = w; } }
.LBB0_567:
	s_and_b64 s[16:17], s[50:51], exec
	s_mov_b32 s13, 0x16c58000
	s_cselect_b32 s13, s13, 0x7c58000
	s_add_u32 s16, s74, s13
	s_addc_u32 s17, s75, 0
	s_and_b64 s[18:19], s[50:51], exec
	s_movk_i32 s13, 0xc00
	s_cselect_b32 s13, s13, 0x1e00
	v_lshl_add_u32 v166, s14, 8, v162
	v_lshl_add_u64 v[138:139], v[156:157], 1, s[16:17]
	v_mad_i64_i32 v[140:141], s[14:15], s13, v166, 0
	v_lshl_add_u64 v[140:141], v[140:141], 1, v[138:139]
	v_pk_add_f32 v[136:137], v[136:137], v[76:77]
	v_pk_add_f32 v[134:135], v[134:135], v[74:75]
	v_pk_add_f32 v[132:133], v[132:133], v[68:69]
	s_and_b64 vcc, exec, s[38:39]
	v_pk_add_f32 v[130:131], v[130:131], v[66:67]
	v_cvt_pk_bf16_f32 v142, v142, v143
	v_cvt_pk_bf16_f32 v143, v144, v145
	v_cvt_pk_bf16_f32 v144, v160, v161
	v_cvt_pk_bf16_f32 v145, v158, v159
	global_store_dwordx4 v[140:141], v[142:145], off sc1
	s_cbranch_vccnz .LBB0_569
	v_mul_f32_e32 v134, 0xbfb8aa3b, v134
	v_mul_f32_e32 v130, 0xbfb8aa3b, v130
	v_mul_f32_e32 v135, 0xbfb8aa3b, v135
	v_mul_f32_e32 v131, 0xbfb8aa3b, v131
	v_mul_f32_e32 v136, 0xbfb8aa3b, v136
	v_mul_f32_e32 v132, 0xbfb8aa3b, v132
	v_mul_f32_e32 v137, 0xbfb8aa3b, v137
	v_mul_f32_e32 v133, 0xbfb8aa3b, v133
	v_exp_f32_e32 v134, v134
	v_exp_f32_e32 v130, v130
	v_exp_f32_e32 v135, v135
	v_exp_f32_e32 v131, v131
	v_exp_f32_e32 v136, v136
	v_exp_f32_e32 v132, v132
	v_exp_f32_e32 v137, v137
	v_exp_f32_e32 v133, v133
	v_add_f32_e32 v134, 1.0, v134
	v_add_f32_e32 v130, 1.0, v130
	v_add_f32_e32 v135, 1.0, v135
	v_add_f32_e32 v131, 1.0, v131
	v_add_f32_e32 v136, 1.0, v136
	v_add_f32_e32 v132, 1.0, v132
	v_add_f32_e32 v137, 1.0, v137
	v_add_f32_e32 v133, 1.0, v133
	v_rcp_f32_e32 v134, v134
	v_rcp_f32_e32 v130, v130
	v_rcp_f32_e32 v135, v135
	v_rcp_f32_e32 v131, v131
	v_rcp_f32_e32 v136, v136
	v_rcp_f32_e32 v132, v132
	v_rcp_f32_e32 v137, v137
	v_rcp_f32_e32 v133, v133
.LBB0_569:
	v_readlane_b32 s16, v255, 27
	v_cvt_pk_bf16_f32 v134, v134, v135
	v_cvt_pk_bf16_f32 v135, v136, v137
	v_cvt_pk_bf16_f32 v136, v130, v131
	v_pk_add_f32 v[128:129], v[128:129], v[88:89]
	v_pk_add_f32 v[126:127], v[126:127], v[86:87]
	v_pk_add_f32 v[124:125], v[124:125], v[84:85]
	s_and_b64 vcc, exec, s[38:39]
	v_pk_add_f32 v[130:131], v[122:123], v[82:83]
	v_readlane_b32 s17, v255, 28
	v_cvt_pk_bf16_f32 v137, v132, v133
	global_store_dwordx4 v[140:141], v[134:137], off offset:256 sc1
	s_cbranch_vccnz .LBB0_571
	v_mul_f32_e32 v122, 0xbfb8aa3b, v126
	v_exp_f32_e32 v122, v122
	v_mul_f32_e32 v123, 0xbfb8aa3b, v130
	v_exp_f32_e32 v123, v123
	v_mul_f32_e32 v124, 0xbfb8aa3b, v124
	v_add_f32_e32 v122, 1.0, v122
	v_rcp_f32_e32 v126, v122
	v_mul_f32_e32 v122, 0xbfb8aa3b, v127
	v_add_f32_e32 v123, 1.0, v123
	v_exp_f32_e32 v122, v122
	v_mul_f32_e32 v127, 0xbfb8aa3b, v131
	v_exp_f32_e32 v131, v127
	v_rcp_f32_e32 v130, v123
	v_mul_f32_e32 v123, 0xbfb8aa3b, v128
	v_exp_f32_e32 v123, v123
	v_exp_f32_e32 v124, v124
	v_add_f32_e32 v122, 1.0, v122
	v_rcp_f32_e32 v127, v122
	v_add_f32_e32 v122, 1.0, v131
	v_rcp_f32_e32 v131, v122
	v_add_f32_e32 v122, 1.0, v123
	v_mul_f32_e32 v123, 0xbfb8aa3b, v129
	v_rcp_f32_e32 v128, v122
	v_add_f32_e32 v122, 1.0, v124
	v_exp_f32_e32 v123, v123
	v_mul_f32_e32 v124, 0xbfb8aa3b, v125
	v_exp_f32_e32 v125, v124
	v_rcp_f32_e32 v124, v122
	v_add_f32_e32 v122, 1.0, v123
	v_rcp_f32_e32 v129, v122
	v_add_f32_e32 v122, 1.0, v125
	v_rcp_f32_e32 v125, v122
.LBB0_571:
	v_or_b32_e32 v122, 16, v166
	v_mad_i64_i32 v[122:123], s[14:15], s13, v122, 0
	v_lshl_add_u64 v[122:123], v[122:123], 1, v[138:139]
	v_pk_add_f32 v[120:121], v[120:121], v[76:77]
	v_pk_add_f32 v[118:119], v[118:119], v[74:75]
	v_pk_add_f32 v[116:117], v[116:117], v[68:69]
	s_and_b64 vcc, exec, s[38:39]
	v_pk_add_f32 v[114:115], v[114:115], v[66:67]
	v_cvt_pk_bf16_f32 v126, v126, v127
	v_cvt_pk_bf16_f32 v127, v128, v129
	v_cvt_pk_bf16_f32 v128, v130, v131
	v_cvt_pk_bf16_f32 v129, v124, v125
	global_store_dwordx4 v[122:123], v[126:129], off sc1
	s_cbranch_vccnz .LBB0_573
	v_mul_f32_e32 v118, 0xbfb8aa3b, v118
	v_mul_f32_e32 v114, 0xbfb8aa3b, v114
	v_mul_f32_e32 v119, 0xbfb8aa3b, v119
	v_mul_f32_e32 v115, 0xbfb8aa3b, v115
	v_mul_f32_e32 v120, 0xbfb8aa3b, v120
	v_mul_f32_e32 v116, 0xbfb8aa3b, v116
	v_mul_f32_e32 v121, 0xbfb8aa3b, v121
	v_mul_f32_e32 v117, 0xbfb8aa3b, v117
	v_exp_f32_e32 v118, v118
	v_exp_f32_e32 v114, v114
	v_exp_f32_e32 v119, v119
	v_exp_f32_e32 v115, v115
	v_exp_f32_e32 v120, v120
	v_exp_f32_e32 v116, v116
	v_exp_f32_e32 v121, v121
	v_exp_f32_e32 v117, v117
	v_add_f32_e32 v118, 1.0, v118
	v_add_f32_e32 v114, 1.0, v114
	v_add_f32_e32 v119, 1.0, v119
	v_add_f32_e32 v115, 1.0, v115
	v_add_f32_e32 v120, 1.0, v120
	v_add_f32_e32 v116, 1.0, v116
	v_add_f32_e32 v121, 1.0, v121
	v_add_f32_e32 v117, 1.0, v117
	v_rcp_f32_e32 v118, v118
	v_rcp_f32_e32 v114, v114
	v_rcp_f32_e32 v119, v119
	v_rcp_f32_e32 v115, v115
	v_rcp_f32_e32 v120, v120
	v_rcp_f32_e32 v116, v116
	v_rcp_f32_e32 v121, v121
	v_rcp_f32_e32 v117, v117
.LBB0_573:
	v_cvt_pk_bf16_f32 v118, v118, v119
	v_cvt_pk_bf16_f32 v119, v120, v121
	v_cvt_pk_bf16_f32 v120, v114, v115
	v_pk_add_f32 v[112:113], v[112:113], v[88:89]
	v_pk_add_f32 v[110:111], v[110:111], v[86:87]
	v_pk_add_f32 v[108:109], v[108:109], v[84:85]
	s_and_b64 vcc, exec, s[38:39]
	v_pk_add_f32 v[114:115], v[106:107], v[82:83]
	v_cvt_pk_bf16_f32 v121, v116, v117
	global_store_dwordx4 v[122:123], v[118:121], off offset:256 sc1
	s_cbranch_vccnz .LBB0_575
	v_mul_f32_e32 v106, 0xbfb8aa3b, v110
	v_exp_f32_e32 v106, v106
	v_mul_f32_e32 v107, 0xbfb8aa3b, v114
	v_exp_f32_e32 v107, v107
	v_mul_f32_e32 v108, 0xbfb8aa3b, v108
	v_add_f32_e32 v106, 1.0, v106
	v_rcp_f32_e32 v110, v106
	v_mul_f32_e32 v106, 0xbfb8aa3b, v111
	v_add_f32_e32 v107, 1.0, v107
	v_exp_f32_e32 v106, v106
	v_mul_f32_e32 v111, 0xbfb8aa3b, v115
	v_exp_f32_e32 v115, v111
	v_rcp_f32_e32 v114, v107
	v_mul_f32_e32 v107, 0xbfb8aa3b, v112
	v_exp_f32_e32 v107, v107
	v_exp_f32_e32 v108, v108
	v_add_f32_e32 v106, 1.0, v106
	v_rcp_f32_e32 v111, v106
	v_add_f32_e32 v106, 1.0, v115
	v_rcp_f32_e32 v115, v106
	v_add_f32_e32 v106, 1.0, v107
	v_mul_f32_e32 v107, 0xbfb8aa3b, v113
	v_rcp_f32_e32 v112, v106
	v_add_f32_e32 v106, 1.0, v108
	v_exp_f32_e32 v107, v107
	v_mul_f32_e32 v108, 0xbfb8aa3b, v109
	v_exp_f32_e32 v109, v108
	v_rcp_f32_e32 v108, v106
	v_add_f32_e32 v106, 1.0, v107
	v_rcp_f32_e32 v113, v106
	v_add_f32_e32 v106, 1.0, v109
	v_rcp_f32_e32 v109, v106
; __device__ __forceinline__ unsigned cvt_pk_bf16(float lo, float hi) { unsigned r; asm volatile("v_cvt_pk_bf16_f32 %0, %1, %2" : "=v"(r) : "v"(lo), "v"(hi)); return r; }
;     __device__ __forceinline__ void operator()(const f32x4 (&acc)[2][2][4][2], const Unit& u, int wr, int wc, int fr, int fq) const {
;     ...
;         for (int ai = 0; ai < 2; ++ai)
; #pragma unroll
;             for (int m = 0; m < 4; ++m) { bf16_t* rowp = base + (size_t)(row0 + ai * HALF + m * 16) * ld + col0;
; #pragma unroll
;                 for (int bj = 0; bj < 2; ++bj) { f32x4 v0 = acc[ai][bj][m][0] + bv[bj][0], v1 = acc[ai][bj][m][1] + bv[bj][1];
;                     if (sig) {
; #pragma unroll
;                         for (int j = 0; j < 4; ++j) { v0[j] = __builtin_amdgcn_rcpf(1.0f + __expf(-v0[j])); v1[j] = __builtin_amdgcn_rcpf(1.0f + __expf(-v1[j])); } }
;                     u32x4 w; w.x = cvt_pk_bf16(v0[0], v0[1]); w.y = cvt_pk_bf16(v0[2], v0[3]); w.z = cvt_pk_bf16(v1[0], v1[1]); w.w = cvt_pk_bf16(v1[2], v1[3]);
;                     *(u32x4*)(rowp + bj * HALF) = w; } }
.LBB0_575:
	v_or_b32_e32 v106, 32, v166
	v_mad_i64_i32 v[106:107], s[14:15], s13, v106, 0
	v_lshl_add_u64 v[106:107], v[106:107], 1, v[138:139]
	v_pk_add_f32 v[104:105], v[104:105], v[76:77]
	v_pk_add_f32 v[102:103], v[102:103], v[74:75]
	v_pk_add_f32 v[100:101], v[100:101], v[68:69]
	s_and_b64 vcc, exec, s[38:39]
	v_pk_add_f32 v[98:99], v[98:99], v[66:67]
	v_cvt_pk_bf16_f32 v110, v110, v111
	v_cvt_pk_bf16_f32 v111, v112, v113
	v_cvt_pk_bf16_f32 v112, v114, v115
	v_cvt_pk_bf16_f32 v113, v108, v109
	global_store_dwordx4 v[106:107], v[110:113], off sc1
	s_cbranch_vccnz .LBB0_577
	v_mul_f32_e32 v102, 0xbfb8aa3b, v102
	v_mul_f32_e32 v98, 0xbfb8aa3b, v98
	v_mul_f32_e32 v103, 0xbfb8aa3b, v103
	v_mul_f32_e32 v99, 0xbfb8aa3b, v99
	v_mul_f32_e32 v104, 0xbfb8aa3b, v104
	v_mul_f32_e32 v100, 0xbfb8aa3b, v100
	v_mul_f32_e32 v105, 0xbfb8aa3b, v105
	v_mul_f32_e32 v101, 0xbfb8aa3b, v101
	v_exp_f32_e32 v102, v102
	v_exp_f32_e32 v98, v98
	v_exp_f32_e32 v103, v103
	v_exp_f32_e32 v99, v99
	v_exp_f32_e32 v104, v104
	v_exp_f32_e32 v100, v100
	v_exp_f32_e32 v105, v105
	v_exp_f32_e32 v101, v101
	v_add_f32_e32 v102, 1.0, v102
	v_add_f32_e32 v98, 1.0, v98
	v_add_f32_e32 v103, 1.0, v103
	v_add_f32_e32 v99, 1.0, v99
	v_add_f32_e32 v104, 1.0, v104
	v_add_f32_e32 v100, 1.0, v100
	v_add_f32_e32 v105, 1.0, v105
	v_add_f32_e32 v101, 1.0, v101
	v_rcp_f32_e32 v102, v102
	v_rcp_f32_e32 v98, v98
	v_rcp_f32_e32 v103, v103
	v_rcp_f32_e32 v99, v99
	v_rcp_f32_e32 v104, v104
	v_rcp_f32_e32 v100, v100
	v_rcp_f32_e32 v105, v105
	v_rcp_f32_e32 v101, v101
.LBB0_577:
	v_cvt_pk_bf16_f32 v102, v102, v103
	v_cvt_pk_bf16_f32 v103, v104, v105
	v_cvt_pk_bf16_f32 v104, v98, v99
	v_pk_add_f32 v[96:97], v[96:97], v[88:89]
	v_pk_add_f32 v[94:95], v[94:95], v[86:87]
	v_pk_add_f32 v[92:93], v[92:93], v[84:85]
	s_and_b64 vcc, exec, s[38:39]
	v_pk_add_f32 v[98:99], v[90:91], v[82:83]
	v_cvt_pk_bf16_f32 v105, v100, v101
	global_store_dwordx4 v[106:107], v[102:105], off offset:256 sc1
	s_cbranch_vccnz .LBB0_579
	v_mul_f32_e32 v90, 0xbfb8aa3b, v94
	v_exp_f32_e32 v90, v90
	v_mul_f32_e32 v91, 0xbfb8aa3b, v98
	v_exp_f32_e32 v91, v91
	v_mul_f32_e32 v92, 0xbfb8aa3b, v92
	v_add_f32_e32 v90, 1.0, v90
	v_rcp_f32_e32 v94, v90
	v_mul_f32_e32 v90, 0xbfb8aa3b, v95
	v_add_f32_e32 v91, 1.0, v91
	v_exp_f32_e32 v90, v90
	v_mul_f32_e32 v95, 0xbfb8aa3b, v99
	v_exp_f32_e32 v99, v95
	v_rcp_f32_e32 v98, v91
	v_mul_f32_e32 v91, 0xbfb8aa3b, v96
	v_exp_f32_e32 v91, v91
	v_exp_f32_e32 v92, v92
	v_add_f32_e32 v90, 1.0, v90
	v_rcp_f32_e32 v95, v90
	v_add_f32_e32 v90, 1.0, v99
	v_rcp_f32_e32 v99, v90
	v_add_f32_e32 v90, 1.0, v91
	v_mul_f32_e32 v91, 0xbfb8aa3b, v97
	v_rcp_f32_e32 v96, v90
	v_add_f32_e32 v90, 1.0, v92
	v_exp_f32_e32 v91, v91
	v_mul_f32_e32 v92, 0xbfb8aa3b, v93
	v_exp_f32_e32 v93, v92
	v_rcp_f32_e32 v92, v90
	v_add_f32_e32 v90, 1.0, v91
	v_rcp_f32_e32 v97, v90
	v_add_f32_e32 v90, 1.0, v93
	v_rcp_f32_e32 v93, v90
.LBB0_579:
	v_or_b32_e32 v90, 48, v166
	v_mad_i64_i32 v[90:91], s[14:15], s13, v90, 0
	v_lshl_add_u64 v[90:91], v[90:91], 1, v[138:139]
	v_pk_add_f32 v[80:81], v[80:81], v[76:77]
	v_pk_add_f32 v[78:79], v[78:79], v[74:75]
	v_pk_add_f32 v[72:73], v[72:73], v[68:69]
	s_and_b64 vcc, exec, s[38:39]
	v_pk_add_f32 v[70:71], v[70:71], v[66:67]
	v_cvt_pk_bf16_f32 v94, v94, v95
	v_cvt_pk_bf16_f32 v95, v96, v97
	v_cvt_pk_bf16_f32 v96, v98, v99
	v_cvt_pk_bf16_f32 v97, v92, v93
	global_store_dwordx4 v[90:91], v[94:97], off sc1
	s_cbranch_vccnz .LBB0_581
	v_mul_f32_e32 v78, 0xbfb8aa3b, v78
	v_mul_f32_e32 v70, 0xbfb8aa3b, v70
	v_mul_f32_e32 v79, 0xbfb8aa3b, v79
	v_mul_f32_e32 v71, 0xbfb8aa3b, v71
	v_mul_f32_e32 v80, 0xbfb8aa3b, v80
	v_mul_f32_e32 v72, 0xbfb8aa3b, v72
	v_mul_f32_e32 v81, 0xbfb8aa3b, v81
	v_mul_f32_e32 v73, 0xbfb8aa3b, v73
	v_exp_f32_e32 v78, v78
	v_exp_f32_e32 v70, v70
	v_exp_f32_e32 v79, v79
	v_exp_f32_e32 v71, v71
	v_exp_f32_e32 v80, v80
	v_exp_f32_e32 v72, v72
	v_exp_f32_e32 v81, v81
	v_exp_f32_e32 v73, v73
	v_add_f32_e32 v78, 1.0, v78
	v_add_f32_e32 v70, 1.0, v70
	v_add_f32_e32 v79, 1.0, v79
	v_add_f32_e32 v71, 1.0, v71
	v_add_f32_e32 v80, 1.0, v80
	v_add_f32_e32 v72, 1.0, v72
	v_add_f32_e32 v81, 1.0, v81
	v_add_f32_e32 v73, 1.0, v73
	v_rcp_f32_e32 v78, v78
	v_rcp_f32_e32 v70, v70
	v_rcp_f32_e32 v79, v79
	v_rcp_f32_e32 v71, v71
	v_rcp_f32_e32 v80, v80
	v_rcp_f32_e32 v72, v72
	v_rcp_f32_e32 v81, v81
	v_rcp_f32_e32 v73, v73
.LBB0_581:
	v_cvt_pk_bf16_f32 v78, v78, v79
	v_cvt_pk_bf16_f32 v79, v80, v81
	v_cvt_pk_bf16_f32 v80, v70, v71
	v_pk_add_f32 v[64:65], v[64:65], v[88:89]
	v_pk_add_f32 v[62:63], v[62:63], v[86:87]
	v_pk_add_f32 v[60:61], v[60:61], v[84:85]
	s_and_b64 vcc, exec, s[38:39]
	v_pk_add_f32 v[70:71], v[58:59], v[82:83]
	v_cvt_pk_bf16_f32 v81, v72, v73
	global_store_dwordx4 v[90:91], v[78:81], off offset:256 sc1
	s_cbranch_vccnz .LBB0_583
	v_mul_f32_e32 v58, 0xbfb8aa3b, v62
	v_exp_f32_e32 v58, v58
	v_mul_f32_e32 v59, 0xbfb8aa3b, v70
	v_exp_f32_e32 v59, v59
	v_mul_f32_e32 v60, 0xbfb8aa3b, v60
	v_add_f32_e32 v58, 1.0, v58
	v_rcp_f32_e32 v62, v58
	v_mul_f32_e32 v58, 0xbfb8aa3b, v63
	v_add_f32_e32 v59, 1.0, v59
	v_exp_f32_e32 v58, v58
	v_mul_f32_e32 v63, 0xbfb8aa3b, v71
	v_exp_f32_e32 v71, v63
	v_rcp_f32_e32 v70, v59
	v_mul_f32_e32 v59, 0xbfb8aa3b, v64
	v_exp_f32_e32 v59, v59
	v_exp_f32_e32 v60, v60
	v_add_f32_e32 v58, 1.0, v58
	v_rcp_f32_e32 v63, v58
	v_add_f32_e32 v58, 1.0, v71
	v_rcp_f32_e32 v71, v58
	v_add_f32_e32 v58, 1.0, v59
	v_mul_f32_e32 v59, 0xbfb8aa3b, v65
	v_rcp_f32_e32 v64, v58
	v_add_f32_e32 v58, 1.0, v60
	v_exp_f32_e32 v59, v59
	v_mul_f32_e32 v60, 0xbfb8aa3b, v61
	v_exp_f32_e32 v61, v60
	v_rcp_f32_e32 v60, v58
	v_add_f32_e32 v58, 1.0, v59
	v_rcp_f32_e32 v65, v58
	v_add_f32_e32 v58, 1.0, v61
	v_rcp_f32_e32 v61, v58
; __device__ __forceinline__ unsigned cvt_pk_bf16(float lo, float hi) { unsigned r; asm volatile("v_cvt_pk_bf16_f32 %0, %1, %2" : "=v"(r) : "v"(lo), "v"(hi)); return r; }
;     __device__ __forceinline__ void operator()(const f32x4 (&acc)[2][2][4][2], const Unit& u, int wr, int wc, int fr, int fq) const {
;     ...
;         for (int ai = 0; ai < 2; ++ai)
; #pragma unroll
;             for (int m = 0; m < 4; ++m) { bf16_t* rowp = base + (size_t)(row0 + ai * HALF + m * 16) * ld + col0;
; #pragma unroll
;                 for (int bj = 0; bj < 2; ++bj) { f32x4 v0 = acc[ai][bj][m][0] + bv[bj][0], v1 = acc[ai][bj][m][1] + bv[bj][1];
;                     if (sig) {
; #pragma unroll
;                         for (int j = 0; j < 4; ++j) { v0[j] = __builtin_amdgcn_rcpf(1.0f + __expf(-v0[j])); v1[j] = __builtin_amdgcn_rcpf(1.0f + __expf(-v1[j])); } }
;                     u32x4 w; w.x = cvt_pk_bf16(v0[0], v0[1]); w.y = cvt_pk_bf16(v0[2], v0[3]); w.z = cvt_pk_bf16(v1[0], v1[1]); w.w = cvt_pk_bf16(v1[2], v1[3]);
;                     *(u32x4*)(rowp + bj * HALF) = w; } }
.LBB0_583:
	v_add_u32_e32 v58, 0x80, v166
	v_mad_i64_i32 v[58:59], s[14:15], s13, v58, 0
	v_lshl_add_u64 v[58:59], v[58:59], 1, v[138:139]
	v_pk_add_f32 v[56:57], v[56:57], v[76:77]
	v_pk_add_f32 v[54:55], v[54:55], v[74:75]
	v_pk_add_f32 v[52:53], v[52:53], v[68:69]
	s_and_b64 vcc, exec, s[38:39]
	v_pk_add_f32 v[50:51], v[50:51], v[66:67]
	v_cvt_pk_bf16_f32 v62, v62, v63
	v_cvt_pk_bf16_f32 v63, v64, v65
	v_cvt_pk_bf16_f32 v64, v70, v71
	v_cvt_pk_bf16_f32 v65, v60, v61
	global_store_dwordx4 v[58:59], v[62:65], off sc1
	s_cbranch_vccnz .LBB0_585
	v_mul_f32_e32 v54, 0xbfb8aa3b, v54
	v_mul_f32_e32 v50, 0xbfb8aa3b, v50
	v_mul_f32_e32 v55, 0xbfb8aa3b, v55
	v_mul_f32_e32 v51, 0xbfb8aa3b, v51
	v_mul_f32_e32 v56, 0xbfb8aa3b, v56
	v_mul_f32_e32 v52, 0xbfb8aa3b, v52
	v_mul_f32_e32 v57, 0xbfb8aa3b, v57
	v_mul_f32_e32 v53, 0xbfb8aa3b, v53
	v_exp_f32_e32 v54, v54
	v_exp_f32_e32 v50, v50
	v_exp_f32_e32 v55, v55
	v_exp_f32_e32 v51, v51
	v_exp_f32_e32 v56, v56
	v_exp_f32_e32 v52, v52
	v_exp_f32_e32 v57, v57
	v_exp_f32_e32 v53, v53
	v_add_f32_e32 v54, 1.0, v54
	v_add_f32_e32 v50, 1.0, v50
	v_add_f32_e32 v55, 1.0, v55
	v_add_f32_e32 v51, 1.0, v51
	v_add_f32_e32 v56, 1.0, v56
	v_add_f32_e32 v52, 1.0, v52
	v_add_f32_e32 v57, 1.0, v57
	v_add_f32_e32 v53, 1.0, v53
	v_rcp_f32_e32 v54, v54
	v_rcp_f32_e32 v50, v50
	v_rcp_f32_e32 v55, v55
	v_rcp_f32_e32 v51, v51
	v_rcp_f32_e32 v56, v56
	v_rcp_f32_e32 v52, v52
	v_rcp_f32_e32 v57, v57
	v_rcp_f32_e32 v53, v53
.LBB0_585:
	v_cvt_pk_bf16_f32 v54, v54, v55
	v_cvt_pk_bf16_f32 v55, v56, v57
	v_cvt_pk_bf16_f32 v56, v50, v51
	v_pk_add_f32 v[48:49], v[48:49], v[88:89]
	v_pk_add_f32 v[46:47], v[46:47], v[86:87]
	v_pk_add_f32 v[44:45], v[44:45], v[84:85]
	s_and_b64 vcc, exec, s[38:39]
	v_pk_add_f32 v[50:51], v[42:43], v[82:83]
	v_cvt_pk_bf16_f32 v57, v52, v53
	global_store_dwordx4 v[58:59], v[54:57], off offset:256 sc1
	s_cbranch_vccnz .LBB0_587
	v_mul_f32_e32 v42, 0xbfb8aa3b, v46
	v_exp_f32_e32 v42, v42
	v_mul_f32_e32 v43, 0xbfb8aa3b, v50
	v_exp_f32_e32 v43, v43
	v_mul_f32_e32 v44, 0xbfb8aa3b, v44
	v_add_f32_e32 v42, 1.0, v42
	v_rcp_f32_e32 v46, v42
	v_mul_f32_e32 v42, 0xbfb8aa3b, v47
	v_add_f32_e32 v43, 1.0, v43
	v_exp_f32_e32 v42, v42
	v_mul_f32_e32 v47, 0xbfb8aa3b, v51
	v_exp_f32_e32 v51, v47
	v_rcp_f32_e32 v50, v43
	v_mul_f32_e32 v43, 0xbfb8aa3b, v48
	v_exp_f32_e32 v43, v43
	v_exp_f32_e32 v44, v44
	v_add_f32_e32 v42, 1.0, v42
	v_rcp_f32_e32 v47, v42
	v_add_f32_e32 v42, 1.0, v51
	v_rcp_f32_e32 v51, v42
	v_add_f32_e32 v42, 1.0, v43
	v_mul_f32_e32 v43, 0xbfb8aa3b, v49
	v_rcp_f32_e32 v48, v42
	v_add_f32_e32 v42, 1.0, v44
	v_exp_f32_e32 v43, v43
	v_mul_f32_e32 v44, 0xbfb8aa3b, v45
	v_exp_f32_e32 v45, v44
	v_rcp_f32_e32 v44, v42
	v_add_f32_e32 v42, 1.0, v43
	v_rcp_f32_e32 v49, v42
	v_add_f32_e32 v42, 1.0, v45
	v_rcp_f32_e32 v45, v42
.LBB0_587:
	v_add_u32_e32 v42, 0x90, v166
	v_mad_i64_i32 v[42:43], s[14:15], s13, v42, 0
	v_lshl_add_u64 v[42:43], v[42:43], 1, v[138:139]
	v_pk_add_f32 v[40:41], v[40:41], v[76:77]
	v_pk_add_f32 v[38:39], v[38:39], v[74:75]
	v_pk_add_f32 v[36:37], v[36:37], v[68:69]
	s_and_b64 vcc, exec, s[38:39]
	v_pk_add_f32 v[34:35], v[34:35], v[66:67]
	v_cvt_pk_bf16_f32 v46, v46, v47
	v_cvt_pk_bf16_f32 v47, v48, v49
	v_cvt_pk_bf16_f32 v48, v50, v51
	v_cvt_pk_bf16_f32 v49, v44, v45
	global_store_dwordx4 v[42:43], v[46:49], off sc1
	s_cbranch_vccnz .LBB0_589
	v_mul_f32_e32 v38, 0xbfb8aa3b, v38
	v_mul_f32_e32 v34, 0xbfb8aa3b, v34
	v_mul_f32_e32 v39, 0xbfb8aa3b, v39
	v_mul_f32_e32 v35, 0xbfb8aa3b, v35
	v_mul_f32_e32 v40, 0xbfb8aa3b, v40
	v_mul_f32_e32 v36, 0xbfb8aa3b, v36
	v_mul_f32_e32 v41, 0xbfb8aa3b, v41
	v_mul_f32_e32 v37, 0xbfb8aa3b, v37
	v_exp_f32_e32 v38, v38
	v_exp_f32_e32 v34, v34
	v_exp_f32_e32 v39, v39
	v_exp_f32_e32 v35, v35
	v_exp_f32_e32 v40, v40
	v_exp_f32_e32 v36, v36
	v_exp_f32_e32 v41, v41
	v_exp_f32_e32 v37, v37
	v_add_f32_e32 v38, 1.0, v38
	v_add_f32_e32 v34, 1.0, v34
	v_add_f32_e32 v39, 1.0, v39
	v_add_f32_e32 v35, 1.0, v35
	v_add_f32_e32 v40, 1.0, v40
	v_add_f32_e32 v36, 1.0, v36
	v_add_f32_e32 v41, 1.0, v41
	v_add_f32_e32 v37, 1.0, v37
	v_rcp_f32_e32 v38, v38
	v_rcp_f32_e32 v34, v34
	v_rcp_f32_e32 v39, v39
	v_rcp_f32_e32 v35, v35
	v_rcp_f32_e32 v40, v40
	v_rcp_f32_e32 v36, v36
	v_rcp_f32_e32 v41, v41
	v_rcp_f32_e32 v37, v37
.LBB0_589:
	v_cvt_pk_bf16_f32 v38, v38, v39
	v_cvt_pk_bf16_f32 v39, v40, v41
	v_cvt_pk_bf16_f32 v40, v34, v35
	v_pk_add_f32 v[32:33], v[32:33], v[88:89]
	v_pk_add_f32 v[30:31], v[30:31], v[86:87]
	v_pk_add_f32 v[28:29], v[28:29], v[84:85]
	s_and_b64 vcc, exec, s[38:39]
	v_pk_add_f32 v[34:35], v[26:27], v[82:83]
	v_cvt_pk_bf16_f32 v41, v36, v37
	global_store_dwordx4 v[42:43], v[38:41], off offset:256 sc1
	s_cbranch_vccnz .LBB0_591
	v_mul_f32_e32 v26, 0xbfb8aa3b, v30
	v_exp_f32_e32 v26, v26
	v_mul_f32_e32 v27, 0xbfb8aa3b, v34
	v_exp_f32_e32 v27, v27
	v_mul_f32_e32 v28, 0xbfb8aa3b, v28
	v_add_f32_e32 v26, 1.0, v26
	v_rcp_f32_e32 v30, v26
	v_mul_f32_e32 v26, 0xbfb8aa3b, v31
	v_add_f32_e32 v27, 1.0, v27
	v_exp_f32_e32 v26, v26
	v_mul_f32_e32 v31, 0xbfb8aa3b, v35
	v_exp_f32_e32 v35, v31
	v_rcp_f32_e32 v34, v27
	v_mul_f32_e32 v27, 0xbfb8aa3b, v32
	v_exp_f32_e32 v27, v27
	v_exp_f32_e32 v28, v28
	v_add_f32_e32 v26, 1.0, v26
	v_rcp_f32_e32 v31, v26
	v_add_f32_e32 v26, 1.0, v35
	v_rcp_f32_e32 v35, v26
	v_add_f32_e32 v26, 1.0, v27
	v_mul_f32_e32 v27, 0xbfb8aa3b, v33
	v_rcp_f32_e32 v32, v26
	v_add_f32_e32 v26, 1.0, v28
	v_exp_f32_e32 v27, v27
	v_mul_f32_e32 v28, 0xbfb8aa3b, v29
	v_exp_f32_e32 v29, v28
	v_rcp_f32_e32 v28, v26
	v_add_f32_e32 v26, 1.0, v27
	v_rcp_f32_e32 v33, v26
	v_add_f32_e32 v26, 1.0, v29
	v_rcp_f32_e32 v29, v26
; __device__ __forceinline__ unsigned cvt_pk_bf16(float lo, float hi) { unsigned r; asm volatile("v_cvt_pk_bf16_f32 %0, %1, %2" : "=v"(r) : "v"(lo), "v"(hi)); return r; }
; #define PG8_BAR __builtin_amdgcn_s_barrier()
; template <class Epi>
; __device__ __forceinline__ void gemm_phase(LAS unsigned char* lds, const Gemm g, const Order& S, const Epi& E) {
;     ...
;         if (!has_next) break;
;         if constexpr (!Epi::KEEP_ACC) {
; #pragma unroll
;         for (int a = 0; a < 2; ++a)
; #pragma unroll
;             for (int b = 0; b < 2; ++b)
; #pragma unroll
;                 for (int m = 0; m < 4; ++m)
; #pragma unroll
;                     for (int n = 0; n < 2; ++n) acc[a][b][m][n] = (f32x4){0.f, 0.f, 0.f, 0.f};
;         }
;         cur = nxt; cA = nA; cB = nB; ++ui;
;         if (wr == 1) PG8_BAR;
;     __device__ __forceinline__ void operator()(const f32x4 (&acc)[2][2][4][2], const Unit& u, int wr, int wc, int fr, int fq) const {
;     ...
;         for (int ai = 0; ai < 2; ++ai)
; #pragma unroll
;             for (int m = 0; m < 4; ++m) { bf16_t* rowp = base + (size_t)(row0 + ai * HALF + m * 16) * ld + col0;
; #pragma unroll
;                 for (int bj = 0; bj < 2; ++bj) { f32x4 v0 = acc[ai][bj][m][0] + bv[bj][0], v1 = acc[ai][bj][m][1] + bv[bj][1];
;                     if (sig) {
; #pragma unroll
;                         for (int j = 0; j < 4; ++j) { v0[j] = __builtin_amdgcn_rcpf(1.0f + __expf(-v0[j])); v1[j] = __builtin_amdgcn_rcpf(1.0f + __expf(-v1[j])); } }
;                     u32x4 w; w.x = cvt_pk_bf16(v0[0], v0[1]); w.y = cvt_pk_bf16(v0[2], v0[3]); w.z = cvt_pk_bf16(v1[0], v1[1]); w.w = cvt_pk_bf16(v1[2], v1[3]);
;                     *(u32x4*)(rowp + bj * HALF) = w; } }
.LBB0_591:
	v_add_u32_e32 v26, 0xa0, v166
	v_mad_i64_i32 v[26:27], s[14:15], s13, v26, 0
	v_lshl_add_u64 v[26:27], v[26:27], 1, v[138:139]
	v_pk_add_f32 v[24:25], v[24:25], v[76:77]
	v_pk_add_f32 v[22:23], v[22:23], v[74:75]
	v_pk_add_f32 v[20:21], v[20:21], v[68:69]
	s_and_b64 vcc, exec, s[38:39]
	v_pk_add_f32 v[18:19], v[18:19], v[66:67]
	v_cvt_pk_bf16_f32 v30, v30, v31
	v_cvt_pk_bf16_f32 v31, v32, v33
	v_cvt_pk_bf16_f32 v32, v34, v35
	v_cvt_pk_bf16_f32 v33, v28, v29
	global_store_dwordx4 v[26:27], v[30:33], off sc1
	s_cbranch_vccnz .LBB0_593
	v_mul_f32_e32 v22, 0xbfb8aa3b, v22
	v_mul_f32_e32 v18, 0xbfb8aa3b, v18
	v_mul_f32_e32 v23, 0xbfb8aa3b, v23
	v_mul_f32_e32 v19, 0xbfb8aa3b, v19
	v_mul_f32_e32 v24, 0xbfb8aa3b, v24
	v_mul_f32_e32 v20, 0xbfb8aa3b, v20
	v_mul_f32_e32 v25, 0xbfb8aa3b, v25
	v_mul_f32_e32 v21, 0xbfb8aa3b, v21
	v_exp_f32_e32 v22, v22
	v_exp_f32_e32 v18, v18
	v_exp_f32_e32 v23, v23
	v_exp_f32_e32 v19, v19
	v_exp_f32_e32 v24, v24
	v_exp_f32_e32 v20, v20
	v_exp_f32_e32 v25, v25
	v_exp_f32_e32 v21, v21
	v_add_f32_e32 v22, 1.0, v22
	v_add_f32_e32 v18, 1.0, v18
	v_add_f32_e32 v23, 1.0, v23
	v_add_f32_e32 v19, 1.0, v19
	v_add_f32_e32 v24, 1.0, v24
	v_add_f32_e32 v20, 1.0, v20
	v_add_f32_e32 v25, 1.0, v25
	v_add_f32_e32 v21, 1.0, v21
	v_rcp_f32_e32 v22, v22
	v_rcp_f32_e32 v18, v18
	v_rcp_f32_e32 v23, v23
	v_rcp_f32_e32 v19, v19
	v_rcp_f32_e32 v24, v24
	v_rcp_f32_e32 v20, v20
	v_rcp_f32_e32 v25, v25
	v_rcp_f32_e32 v21, v21
.LBB0_593:
	v_cvt_pk_bf16_f32 v22, v22, v23
	v_cvt_pk_bf16_f32 v23, v24, v25
	v_cvt_pk_bf16_f32 v24, v18, v19
	v_pk_add_f32 v[16:17], v[16:17], v[88:89]
	v_pk_add_f32 v[14:15], v[14:15], v[86:87]
	v_pk_add_f32 v[12:13], v[12:13], v[84:85]
	s_and_b64 vcc, exec, s[38:39]
	v_pk_add_f32 v[18:19], v[10:11], v[82:83]
	v_cvt_pk_bf16_f32 v25, v20, v21
	global_store_dwordx4 v[26:27], v[22:25], off offset:256 sc1
	s_cbranch_vccnz .LBB0_595
	v_mul_f32_e32 v10, 0xbfb8aa3b, v14
	v_exp_f32_e32 v10, v10
	v_mul_f32_e32 v11, 0xbfb8aa3b, v18
	v_exp_f32_e32 v11, v11
	v_mul_f32_e32 v12, 0xbfb8aa3b, v12
	v_add_f32_e32 v10, 1.0, v10
	v_rcp_f32_e32 v14, v10
	v_mul_f32_e32 v10, 0xbfb8aa3b, v15
	v_add_f32_e32 v11, 1.0, v11
	v_exp_f32_e32 v10, v10
	v_mul_f32_e32 v15, 0xbfb8aa3b, v19
	v_exp_f32_e32 v19, v15
	v_rcp_f32_e32 v18, v11
	v_mul_f32_e32 v11, 0xbfb8aa3b, v16
	v_exp_f32_e32 v11, v11
	v_exp_f32_e32 v12, v12
	v_add_f32_e32 v10, 1.0, v10
	v_rcp_f32_e32 v15, v10
	v_add_f32_e32 v10, 1.0, v19
	v_rcp_f32_e32 v19, v10
	v_add_f32_e32 v10, 1.0, v11
	v_mul_f32_e32 v11, 0xbfb8aa3b, v17
	v_rcp_f32_e32 v16, v10
	v_add_f32_e32 v10, 1.0, v12
	v_exp_f32_e32 v11, v11
	v_mul_f32_e32 v12, 0xbfb8aa3b, v13
	v_exp_f32_e32 v13, v12
	v_rcp_f32_e32 v12, v10
	v_add_f32_e32 v10, 1.0, v11
	v_rcp_f32_e32 v17, v10
	v_add_f32_e32 v10, 1.0, v13
	v_rcp_f32_e32 v13, v10
.LBB0_595:
	v_add_u32_e32 v10, 0xb0, v166
	v_mad_i64_i32 v[10:11], s[14:15], s13, v10, 0
	v_lshl_add_u64 v[10:11], v[10:11], 1, v[138:139]
	v_pk_add_f32 v[8:9], v[8:9], v[76:77]
	v_pk_add_f32 v[6:7], v[6:7], v[74:75]
	v_pk_add_f32 v[4:5], v[4:5], v[68:69]
	s_and_b64 vcc, exec, s[38:39]
	v_pk_add_f32 v[2:3], v[2:3], v[66:67]
	v_cvt_pk_bf16_f32 v14, v14, v15
	v_cvt_pk_bf16_f32 v15, v16, v17
	v_cvt_pk_bf16_f32 v16, v18, v19
	v_cvt_pk_bf16_f32 v17, v12, v13
	global_store_dwordx4 v[10:11], v[14:17], off sc1
	s_cbranch_vccnz .LBB0_597
	v_mul_f32_e32 v6, 0xbfb8aa3b, v6
	v_mul_f32_e32 v2, 0xbfb8aa3b, v2
	v_mul_f32_e32 v7, 0xbfb8aa3b, v7
	v_mul_f32_e32 v3, 0xbfb8aa3b, v3
	v_mul_f32_e32 v8, 0xbfb8aa3b, v8
	v_mul_f32_e32 v4, 0xbfb8aa3b, v4
	v_mul_f32_e32 v9, 0xbfb8aa3b, v9
	v_mul_f32_e32 v5, 0xbfb8aa3b, v5
	v_exp_f32_e32 v6, v6
	v_exp_f32_e32 v2, v2
	v_exp_f32_e32 v7, v7
	v_exp_f32_e32 v3, v3
	v_exp_f32_e32 v8, v8
	v_exp_f32_e32 v4, v4
	v_exp_f32_e32 v9, v9
	v_exp_f32_e32 v5, v5
	v_add_f32_e32 v6, 1.0, v6
	v_add_f32_e32 v2, 1.0, v2
	v_add_f32_e32 v7, 1.0, v7
	v_add_f32_e32 v3, 1.0, v3
	v_add_f32_e32 v8, 1.0, v8
	v_add_f32_e32 v4, 1.0, v4
	v_add_f32_e32 v9, 1.0, v9
	v_add_f32_e32 v5, 1.0, v5
	v_rcp_f32_e32 v6, v6
	v_rcp_f32_e32 v2, v2
	v_rcp_f32_e32 v7, v7
	v_rcp_f32_e32 v3, v3
	v_rcp_f32_e32 v8, v8
	v_rcp_f32_e32 v4, v4
	v_rcp_f32_e32 v9, v9
	v_rcp_f32_e32 v5, v5
.LBB0_597:
	s_andn2_b64 vcc, exec, s[36:37]
	s_mov_b64 s[36:37], -1
	v_cvt_pk_bf16_f32 v6, v6, v7
	v_cvt_pk_bf16_f32 v7, v8, v9
	v_cvt_pk_bf16_f32 v8, v2, v3
	v_cvt_pk_bf16_f32 v9, v4, v5
	global_store_dwordx4 v[10:11], v[6:9], off offset:256 sc1
	s_cbranch_vccnz .LBB0_550
	s_andn2_b64 vcc, exec, s[0:1]
	s_cbranch_vccnz .LBB0_549
	s_barrier
	s_branch .LBB0_549
